# re-measure of v159 (job placement by XCD, contiguous S5 groups)
# baseline (speedup 1.0000x reference)
;   __shared__ int sjob;
;   if (mode & 1)
;   for (int jb = blockIdx.x; jb < 176; jb += gridDim.x) {
;     if (jb < 48) { if (EN & 16) s5_job(p, l, jb, smem); }
;     else { if (EN & 32) mlstm_job(p, l, jb - 48, smem); }
;   }
.LBB0_421:
	s_mov_b64 s[0:1], 0
	v_writelane_b32 v255, s0, 22
	s_andn2_b64 vcc, exec, s[4:5]
	s_nop 0
	v_writelane_b32 v255, s1, 23
	s_cbranch_vccnz .LBB0_605
	v_readlane_b32 s0, v255, 24
	s_cmp_gt_i32 s0, 0
	s_mov_b64 s[4:5], -1
	s_cbranch_scc0 .LBB0_603
	v_readlane_b32 s0, v252, 0
	s_cmpk_lg_i32 s83, 0x100
	s_cbranch_scc1 .Ljm_plain
	s_and_b32 s38, s0, 7
	s_lshr_b32 vcc_lo, s0, 3
	s_and_b32 vcc_hi, s38, 3
	s_cmp_eq_u32 vcc_hi, 0
	s_cbranch_scc0 .Ljm_ml
	s_lshr_b32 s38, s38, 2
	s_mul_i32 s38, s38, 24
	s_add_i32 s38, s38, vcc_lo
	s_cmp_lt_u32 vcc_lo, 24
	s_cselect_b32 s38, s38, 0x100
	s_branch .Ljm_done
.Ljm_ml:
	s_cmp_gt_u32 s38, 4
	s_cselect_b32 vcc_hi, 2, 1
	s_sub_u32 s38, s38, vcc_hi
	s_mul_i32 vcc_lo, vcc_lo, 6
	s_add_i32 s38, s38, vcc_lo
	s_add_i32 s38, s38, 48
	s_cmpk_lt_u32 s38, 0xb0
	s_cselect_b32 s38, s38, 0x100
	s_branch .Ljm_done

; #define TIDX(p) ((p).wv * 64 + (int)__builtin_amdgcn_mbcnt_hi(~0u, __builtin_amdgcn_mbcnt_lo(~0u, 0u)))
;     ...
;   unsigned* cnt = (unsigned*)(p.ws + OFF_CNT) + slot;
;   const int nj = (mode & 2) ? ((l == 0) ? 1536 : 768) : 0;
;   while (true) {
;     __syncthreads();
;     if (TIDX(p) == 0) sjob = (int)atomicAdd(cnt, 1u);
;     __syncthreads();
;     const int j = sjob;
;     if (j >= nj) break;
;     if (j < 768) { if (EN & 64) hyena_job<2048>(p, l, j, smem); }
;     else { if (EN & 128) hyena_job<256>(p, l, j - 768, smem); }
;   }
.LBB0_514:
	v_readlane_b32 s4, v255, 20
	v_readlane_b32 s5, v255, 21
	s_lshl_b64 s[0:1], s[4:5], 2
	v_readlane_b32 s2, v253, 35
	v_readlane_b32 s3, v253, 36
	s_add_u32 s0, s2, s0
	s_addc_u32 s1, s3, s1
	v_readlane_b32 s2, v255, 60
	v_readlane_b32 s3, v255, 9
	s_lshr_b32 s2, s2, s3
	s_and_b32 s2, s2, 1
	s_lshl_b32 s2, s2, 3
	s_add_u32 s0, s0, s2
	s_addc_u32 s1, s1, 0
	v_writelane_b32 v255, s0, 27
	v_readlane_b32 s2, v253, 53
	v_readlane_b32 s3, v253, 54
	v_writelane_b32 v255, s1, 28
	s_and_b64 s[0:1], s[46:47], exec
	s_mul_i32 s1, s4, 0xc00000
	s_cselect_b32 s60, s81, 0x300
	s_mul_hi_i32 s0, s4, 0xc00000
	s_add_u32 s1, s2, s1
	v_writelane_b32 v255, s1, 10
	s_addc_u32 s0, s3, s0
	v_writelane_b32 v255, s0, 22
	s_mul_i32 s73, s4, 0x900
	v_sub_u32_e32 v0, 0, v211
	v_readlane_b32 s0, v255, 7
	s_mul_i32 s61, s4, 0x1b00
	s_mul_i32 s74, s4, 0xffffee00
	v_cmp_eq_u32_e64 s[68:69], s0, v0
	s_ashr_i32 s0, s73, 31
	v_writelane_b32 v255, s0, 15
	s_mov_b32 s83, s70
	s_ashr_i32 s75, s70, 31
	s_mul_i32 s76, s4, 0xfffffd00
	s_mul_i32 s77, s4, 0xffffeb00
	s_branch .LBB0_517

; DI f32x4 mfma16(bf16x8 a, bf16x8 b, f32x4 c) { return __builtin_amdgcn_mfma_f32_16x16x32_bf16(a, b, c, 0, 0, 0); }
; template <int L, int TPW>
; DI void hy_mfma(const PX& p, f32x4 (&acc)[TPW], const bfu* cp, const bfu* U) {
;     ...
;   if constexpr (TPW == 16) {
;     bf16x8 F[16];
; #pragma unroll
;     for (int m = 0; m < 16; m++) F[m] = *(const bf16x8*)(cpe + 8 * (qb0 - 2 * m));
; #pragma unroll 1
;     for (int k = 0; k < NS / 8; k++) {
; #pragma unroll
;       for (int j = 0; j < 8; j++) {
;         const int ss = 8 * k + j;
;         const int qb = qb0 + 4 * ss;
;         F[(0 - 2 * j) & 15] = *(const bf16x8*)(cpe + 8 * qb);
;         F[(1 - 2 * j) & 15] = *(const bf16x8*)(cpe + 8 * (qb - 2));
;         const bf16x8 bfr = *(const bf16x8*)(Ub + 32 * ss);
; #pragma unroll
;         for (int m = 0; m < 16; m++) acc[m] = mfma16(F[(m - 2 * j) & 15], bfr, acc[m]);
;       }
;     }
.LBB0_584:
	v_add_u32_e32 v133, s0, v130
	v_add_u32_e32 v132, 0x10100, v133
	ds_read_b128 v[134:137], v132
	v_add_u32_e32 v132, s0, v131
	s_addk_i32 s0, 0x200
	s_cmpk_lg_i32 s0, 0x1000
	s_waitcnt lgkmcnt(0)
	v_mfma_f32_16x16x32_bf16 v[6:9], v[74:77], v[134:137], v[6:9]
	v_mfma_f32_16x16x32_bf16 v[74:77], v[82:85], v[134:137], v[2:5]
	s_nop 2
	ds_read_b128 v[2:5], v132 offset:32
	v_mfma_f32_16x16x32_bf16 v[138:141], v[62:65], v[134:137], v[50:53]
	s_nop 2
	ds_read_b128 v[50:53], v132
	s_waitcnt lgkmcnt(1)
	v_mfma_f32_16x16x32_bf16 v[82:85], v[2:5], v[134:137], v[118:121]
	s_nop 2
	v_add_u32_e32 v118, 0x10140, v133
	ds_read_b128 v[118:121], v118
	v_mfma_f32_16x16x32_bf16 v[14:17], v[86:89], v[134:137], v[14:17]
	s_waitcnt lgkmcnt(0)
	v_mfma_f32_16x16x32_bf16 v[6:9], v[86:89], v[118:121], v[6:9]
	v_add_u32_e32 v86, 0x10180, v133
	v_mfma_f32_16x16x32_bf16 v[54:57], v[58:61], v[134:137], v[54:57]
	v_mfma_f32_16x16x32_bf16 v[46:49], v[66:69], v[134:137], v[46:49]
	v_mfma_f32_16x16x32_bf16 v[42:45], v[90:93], v[134:137], v[42:45]
	v_mfma_f32_16x16x32_bf16 v[38:41], v[70:73], v[134:137], v[38:41]
	v_mfma_f32_16x16x32_bf16 v[34:37], v[78:81], v[134:137], v[34:37]
	v_mfma_f32_16x16x32_bf16 v[30:33], v[98:101], v[134:137], v[30:33]
	v_mfma_f32_16x16x32_bf16 v[26:29], v[110:113], v[134:137], v[26:29]
	v_mfma_f32_16x16x32_bf16 v[22:25], v[102:105], v[134:137], v[22:25]
	v_mfma_f32_16x16x32_bf16 v[18:21], v[106:109], v[134:137], v[18:21]
	v_mfma_f32_16x16x32_bf16 v[10:13], v[94:97], v[134:137], v[10:13]
	v_mfma_f32_16x16x32_bf16 v[114:117], v[50:53], v[134:137], v[114:117]
	v_mfma_f32_16x16x32_bf16 v[134:137], v[50:53], v[118:121], v[138:141]
	s_nop 2
	ds_read_b128 v[138:141], v86
	v_mfma_f32_16x16x32_bf16 v[74:77], v[94:97], v[118:121], v[74:77]
	s_waitcnt lgkmcnt(0)
	v_mfma_f32_16x16x32_bf16 v[86:89], v[106:109], v[138:141], v[74:77]
	v_mfma_f32_16x16x32_bf16 v[14:17], v[102:105], v[118:121], v[14:17]
	s_nop 4
	ds_read_b128 v[74:77], v132 offset:96
	s_waitcnt lgkmcnt(0)
	v_mfma_f32_16x16x32_bf16 v[94:97], v[74:77], v[118:121], v[82:85]
	s_nop 2
	ds_read_b128 v[82:85], v132 offset:64
	v_mfma_f32_16x16x32_bf16 v[6:9], v[102:105], v[138:141], v[6:9]
	s_waitcnt lgkmcnt(0)
	v_mfma_f32_16x16x32_bf16 v[102:105], v[82:85], v[118:121], v[114:117]
	s_nop 2
	v_add_u32_e32 v114, 0x101c0, v133
	ds_read_b128 v[114:117], v114
	v_mfma_f32_16x16x32_bf16 v[22:25], v[98:101], v[118:121], v[22:25]
	v_mfma_f32_16x16x32_bf16 v[14:17], v[98:101], v[138:141], v[14:17]
	s_waitcnt lgkmcnt(0)
	v_mfma_f32_16x16x32_bf16 v[6:9], v[98:101], v[114:117], v[6:9]
	v_mfma_f32_16x16x32_bf16 v[98:101], v[110:113], v[114:117], v[86:89]
	s_nop 2
	ds_read_b128 v[86:89], v132 offset:160
	v_mfma_f32_16x16x32_bf16 v[10:13], v[106:109], v[118:121], v[10:13]
	v_mfma_f32_16x16x32_bf16 v[18:21], v[110:113], v[118:121], v[18:21]
	v_mfma_f32_16x16x32_bf16 v[10:13], v[110:113], v[138:141], v[10:13]
	s_waitcnt lgkmcnt(0)
	v_mfma_f32_16x16x32_bf16 v[110:113], v[86:89], v[138:141], v[94:97]
	s_nop 2
	ds_read_b128 v[94:97], v132 offset:128
	v_mfma_f32_16x16x32_bf16 v[54:57], v[2:5], v[118:121], v[54:57]
	v_mfma_f32_16x16x32_bf16 v[46:49], v[58:61], v[118:121], v[46:49]
	v_mfma_f32_16x16x32_bf16 v[42:45], v[62:65], v[118:121], v[42:45]
	v_mfma_f32_16x16x32_bf16 v[38:41], v[66:69], v[118:121], v[38:41]
	v_mfma_f32_16x16x32_bf16 v[34:37], v[90:93], v[118:121], v[34:37]
	v_mfma_f32_16x16x32_bf16 v[30:33], v[70:73], v[118:121], v[30:33]
	v_mfma_f32_16x16x32_bf16 v[26:29], v[78:81], v[118:121], v[26:29]
	v_mfma_f32_16x16x32_bf16 v[106:109], v[82:85], v[138:141], v[134:137]
	s_waitcnt lgkmcnt(0)
	v_mfma_f32_16x16x32_bf16 v[118:121], v[94:97], v[138:141], v[102:105]
	s_nop 2
	v_add_u32_e32 v102, 0x10200, v133
	v_mfma_f32_16x16x32_bf16 v[46:49], v[2:5], v[138:141], v[46:49]
	v_mfma_f32_16x16x32_bf16 v[42:45], v[50:53], v[138:141], v[42:45]
	v_mfma_f32_16x16x32_bf16 v[38:41], v[58:61], v[138:141], v[38:41]
	v_mfma_f32_16x16x32_bf16 v[34:37], v[62:65], v[138:141], v[34:37]
	v_mfma_f32_16x16x32_bf16 v[30:33], v[66:69], v[138:141], v[30:33]
	v_mfma_f32_16x16x32_bf16 v[26:29], v[90:93], v[138:141], v[26:29]
	v_mfma_f32_16x16x32_bf16 v[22:25], v[70:73], v[138:141], v[22:25]
	v_mfma_f32_16x16x32_bf16 v[18:21], v[78:81], v[138:141], v[18:21]
	v_mfma_f32_16x16x32_bf16 v[54:57], v[74:77], v[138:141], v[54:57]
	ds_read_b128 v[138:141], v102
	v_mfma_f32_16x16x32_bf16 v[134:137], v[94:97], v[114:117], v[106:109]
	s_nop 2
	ds_read_b128 v[106:109], v132 offset:192
	ds_read_b128 v[102:105], v132 offset:224
	v_mfma_f32_16x16x32_bf16 v[14:17], v[70:73], v[114:117], v[14:17]
	s_waitcnt lgkmcnt(2)
	v_mfma_f32_16x16x32_bf16 v[6:9], v[70:73], v[138:141], v[6:9]
	v_mfma_f32_16x16x32_bf16 v[70:73], v[78:81], v[138:141], v[98:101]
	s_nop 2
	v_add_u32_e32 v98, 0x10240, v133
	v_mfma_f32_16x16x32_bf16 v[46:49], v[74:77], v[114:117], v[46:49]
	v_mfma_f32_16x16x32_bf16 v[42:45], v[82:85], v[114:117], v[42:45]
	v_mfma_f32_16x16x32_bf16 v[38:41], v[2:5], v[114:117], v[38:41]
	v_mfma_f32_16x16x32_bf16 v[34:37], v[50:53], v[114:117], v[34:37]
	v_mfma_f32_16x16x32_bf16 v[30:33], v[58:61], v[114:117], v[30:33]
	v_mfma_f32_16x16x32_bf16 v[26:29], v[62:65], v[114:117], v[26:29]
	v_mfma_f32_16x16x32_bf16 v[22:25], v[66:69], v[114:117], v[22:25]
	v_mfma_f32_16x16x32_bf16 v[18:21], v[90:93], v[114:117], v[18:21]
	v_mfma_f32_16x16x32_bf16 v[10:13], v[78:81], v[114:117], v[10:13]
	v_mfma_f32_16x16x32_bf16 v[54:57], v[86:89], v[114:117], v[54:57]
	s_waitcnt lgkmcnt(0)
; DI f32x4 mfma16(bf16x8 a, bf16x8 b, f32x4 c) { return __builtin_amdgcn_mfma_f32_16x16x32_bf16(a, b, c, 0, 0, 0); }
; template <int L, int TPW>
; DI void hy_mfma(const PX& p, f32x4 (&acc)[TPW], const bfu* cp, const bfu* U) {
;     ...
;   if constexpr (TPW == 16) {
;     bf16x8 F[16];
; #pragma unroll
;     for (int m = 0; m < 16; m++) F[m] = *(const bf16x8*)(cpe + 8 * (qb0 - 2 * m));
; #pragma unroll 1
;     for (int k = 0; k < NS / 8; k++) {
; #pragma unroll
;       for (int j = 0; j < 8; j++) {
;         const int ss = 8 * k + j;
;         const int qb = qb0 + 4 * ss;
;         F[(0 - 2 * j) & 15] = *(const bf16x8*)(cpe + 8 * qb);
;         F[(1 - 2 * j) & 15] = *(const bf16x8*)(cpe + 8 * (qb - 2));
;         const bf16x8 bfr = *(const bf16x8*)(Ub + 32 * ss);
; #pragma unroll
;         for (int m = 0; m < 16; m++) acc[m] = mfma16(F[(m - 2 * j) & 15], bfr, acc[m]);
;       }
;     }
	v_mfma_f32_16x16x32_bf16 v[78:81], v[102:105], v[114:117], v[110:113]
	v_mfma_f32_16x16x32_bf16 v[114:117], v[106:109], v[114:117], v[118:121]
	s_nop 1
	ds_read_b128 v[110:113], v132 offset:256
	v_mfma_f32_16x16x32_bf16 v[118:121], v[106:109], v[138:141], v[134:137]
	s_nop 2
	ds_read_b128 v[134:137], v98
	ds_read_b128 v[98:101], v132 offset:288
	v_mfma_f32_16x16x32_bf16 v[14:17], v[66:69], v[138:141], v[14:17]
	s_waitcnt lgkmcnt(1)
	v_mfma_f32_16x16x32_bf16 v[6:9], v[66:69], v[134:137], v[6:9]
	v_mfma_f32_16x16x32_bf16 v[66:69], v[90:93], v[134:137], v[70:73]
	s_nop 2
	v_add_u32_e32 v70, 0x10280, v133
	v_mfma_f32_16x16x32_bf16 v[10:13], v[90:93], v[138:141], v[10:13]
	v_mfma_f32_16x16x32_bf16 v[90:93], v[110:113], v[138:141], v[114:117]
	v_mfma_f32_16x16x32_bf16 v[114:117], v[110:113], v[134:137], v[118:121]
	s_nop 2
	ds_read_b128 v[118:121], v70
	ds_read_b128 v[70:73], v132 offset:352
	s_waitcnt lgkmcnt(2)
	v_mfma_f32_16x16x32_bf16 v[78:81], v[98:101], v[138:141], v[78:81]
	v_mfma_f32_16x16x32_bf16 v[22:25], v[58:61], v[138:141], v[22:25]
	v_mfma_f32_16x16x32_bf16 v[18:21], v[62:65], v[138:141], v[18:21]
	v_mfma_f32_16x16x32_bf16 v[14:17], v[58:61], v[134:137], v[14:17]
	v_mfma_f32_16x16x32_bf16 v[10:13], v[62:65], v[134:137], v[10:13]
	s_waitcnt lgkmcnt(1)
	v_mfma_f32_16x16x32_bf16 v[6:9], v[58:61], v[118:121], v[6:9]
	v_mfma_f32_16x16x32_bf16 v[58:61], v[62:65], v[118:121], v[66:69]
	s_waitcnt lgkmcnt(0)
	v_mfma_f32_16x16x32_bf16 v[62:65], v[70:73], v[134:137], v[78:81]
	s_nop 0
	v_add_u32_e32 v66, 0x102c0, v133
	s_nop 0
	ds_read_b128 v[78:81], v132 offset:320
	v_mfma_f32_16x16x32_bf16 v[46:49], v[86:89], v[138:141], v[46:49]
	v_mfma_f32_16x16x32_bf16 v[42:45], v[94:97], v[138:141], v[42:45]
	v_mfma_f32_16x16x32_bf16 v[38:41], v[74:77], v[138:141], v[38:41]
	v_mfma_f32_16x16x32_bf16 v[34:37], v[82:85], v[138:141], v[34:37]
	v_mfma_f32_16x16x32_bf16 v[30:33], v[2:5], v[138:141], v[30:33]
	v_mfma_f32_16x16x32_bf16 v[26:29], v[50:53], v[138:141], v[26:29]
	v_mfma_f32_16x16x32_bf16 v[54:57], v[102:105], v[138:141], v[54:57]
	ds_read_b128 v[138:141], v66
	ds_read_b128 v[66:69], v132 offset:416
	v_mfma_f32_16x16x32_bf16 v[46:49], v[102:105], v[134:137], v[46:49]
	v_mfma_f32_16x16x32_bf16 v[42:45], v[106:109], v[134:137], v[42:45]
	v_mfma_f32_16x16x32_bf16 v[38:41], v[86:89], v[134:137], v[38:41]
	v_mfma_f32_16x16x32_bf16 v[34:37], v[94:97], v[134:137], v[34:37]
	v_mfma_f32_16x16x32_bf16 v[30:33], v[74:77], v[134:137], v[30:33]
	v_mfma_f32_16x16x32_bf16 v[26:29], v[82:85], v[134:137], v[26:29]
	v_mfma_f32_16x16x32_bf16 v[22:25], v[2:5], v[134:137], v[22:25]
	v_mfma_f32_16x16x32_bf16 v[18:21], v[50:53], v[134:137], v[18:21]
	v_mfma_f32_16x16x32_bf16 v[54:57], v[98:101], v[134:137], v[54:57]
	v_mfma_f32_16x16x32_bf16 v[14:17], v[2:5], v[118:121], v[14:17]
	s_waitcnt lgkmcnt(2)
	v_mfma_f32_16x16x32_bf16 v[134:137], v[78:81], v[134:137], v[90:93]
	s_waitcnt lgkmcnt(1)
	v_mfma_f32_16x16x32_bf16 v[6:9], v[2:5], v[138:141], v[6:9]
	s_nop 0
	ds_read_b128 v[90:93], v132 offset:384
	v_mfma_f32_16x16x32_bf16 v[2:5], v[50:53], v[138:141], v[58:61]
	s_nop 2
	ds_read_b128 v[58:61], v132 offset:480
	s_waitcnt lgkmcnt(2)
	v_mfma_f32_16x16x32_bf16 v[62:65], v[66:69], v[118:121], v[62:65]
	v_mfma_f32_16x16x32_bf16 v[46:49], v[98:101], v[118:121], v[46:49]
	v_mfma_f32_16x16x32_bf16 v[42:45], v[110:113], v[118:121], v[42:45]
	v_mfma_f32_16x16x32_bf16 v[38:41], v[102:105], v[118:121], v[38:41]
	v_mfma_f32_16x16x32_bf16 v[34:37], v[106:109], v[118:121], v[34:37]
	v_mfma_f32_16x16x32_bf16 v[30:33], v[86:89], v[118:121], v[30:33]
	v_mfma_f32_16x16x32_bf16 v[26:29], v[94:97], v[118:121], v[26:29]
	v_mfma_f32_16x16x32_bf16 v[22:25], v[74:77], v[118:121], v[22:25]
	v_mfma_f32_16x16x32_bf16 v[18:21], v[82:85], v[118:121], v[18:21]
	v_mfma_f32_16x16x32_bf16 v[10:13], v[50:53], v[118:121], v[10:13]
	v_mfma_f32_16x16x32_bf16 v[54:57], v[70:73], v[118:121], v[54:57]
	v_mfma_f32_16x16x32_bf16 v[114:117], v[78:81], v[118:121], v[114:117]
	s_waitcnt lgkmcnt(1)
	v_mfma_f32_16x16x32_bf16 v[134:137], v[90:93], v[118:121], v[134:137]
	s_waitcnt lgkmcnt(0)
	v_mfma_f32_16x16x32_bf16 v[118:121], v[58:61], v[138:141], v[62:65]
	s_nop 2
	ds_read_b128 v[62:65], v132 offset:448
	v_mfma_f32_16x16x32_bf16 v[46:49], v[70:73], v[138:141], v[46:49]
	v_mfma_f32_16x16x32_bf16 v[42:45], v[78:81], v[138:141], v[42:45]
	v_mfma_f32_16x16x32_bf16 v[38:41], v[98:101], v[138:141], v[38:41]
	v_mfma_f32_16x16x32_bf16 v[34:37], v[110:113], v[138:141], v[34:37]
	v_mfma_f32_16x16x32_bf16 v[30:33], v[102:105], v[138:141], v[30:33]
	v_mfma_f32_16x16x32_bf16 v[26:29], v[106:109], v[138:141], v[26:29]
	v_mfma_f32_16x16x32_bf16 v[22:25], v[86:89], v[138:141], v[22:25]
	v_mfma_f32_16x16x32_bf16 v[18:21], v[94:97], v[138:141], v[18:21]
	v_mfma_f32_16x16x32_bf16 v[14:17], v[74:77], v[138:141], v[14:17]
	v_mfma_f32_16x16x32_bf16 v[10:13], v[82:85], v[138:141], v[10:13]
	v_mfma_f32_16x16x32_bf16 v[54:57], v[66:69], v[138:141], v[54:57]
	v_mfma_f32_16x16x32_bf16 v[50:53], v[90:93], v[138:141], v[114:117]
	s_waitcnt lgkmcnt(0)
	v_mfma_f32_16x16x32_bf16 v[114:117], v[62:65], v[138:141], v[134:137]
	s_cbranch_scc1 .LBB0_584
; #define OPAQUE(x) asm volatile("" : "+v"(x))
; DI float bf2f(bfu v) { return __uint_as_float(((unsigned)v) << 16); }
; DI unsigned pack2(float a, float b) { f32x2_t v = {a, b}; bf16x2_t r = __builtin_convertvector(v, bf16x2_t); return __builtin_bit_cast(unsigned, r); }
; DI float lo16(unsigned u) { return __uint_as_float(u << 16); }
; DI float hi16(unsigned u) { return __uint_as_float(u & 0xffff0000u); }
; template <int L>
; DI void hyena_job(const PX& p, int l, int c, unsigned char* smem) {
;     ...
;   {
;     f32x4 acc[TPW];
;     hy_mfma<L, TPW>(p, acc, cp, U);
;     bfu* yrow = (bfu*)zv;
;     int kq_o = kq;
;     OPAQUE(kq_o);
; #pragma unroll
;     for (int m = 0; m < TPW; m++) {
;       const int t0 = 16 * (w * TPW + m) + 4 * kq_o;
;       const bfu* zr = zx2 + b * L;
;       const uint2 mid = *(const uint2*)(zr + t0);
;       const bool lv = (t0 % RL != 0), rv = ((t0 + 4) % RL != 0);
;       const float lft = bf2f(zr[lv ? t0 - 1 : t0]) * (lv ? 1.f : 0.f);
;       const float rgt = bf2f(zr[rv ? t0 + 4 : t0]) * (rv ? 1.f : 0.f);
;       float z[6];
;       z[0] = lft; z[5] = rgt; z[1] = lo16(mid.x); z[2] = hi16(mid.x); z[3] = lo16(mid.y); z[4] = hi16(mid.y);
;       const uint2 vu = *(const uint2*)(U + b * USTR + t0);
;       const float vv[4] = {lo16(vu.x), hi16(vu.x), lo16(vu.y), hi16(vu.y)};
;       float y2[4];
; #pragma unroll
;       for (int r = 0; r < 4; r++) {
;         const float x2 = w2[0] * z[r] + w2[1] * z[r + 1] + w2[2] * z[r + 2] + w2[3];
;         y2[r] = x2 * (acc[m][r] + bias1 * vv[r]);
;       }
;       uint2 o2; o2.x = pack2(y2[0], y2[1]); o2.y = pack2(y2[2], y2[3]);
;       *(uint2*)(yrow + b * L + t0) = o2;
;     }
	s_waitcnt vmcnt(0)
	s_mul_hi_i32 s1, s70, 0x12000
	s_mul_i32 s70, s70, 0x12000
	v_readlane_b32 s2, v253, 29
	v_readlane_b32 s3, v253, 30
	s_add_u32 s0, s2, s70
	s_addc_u32 s1, s3, s1
	v_lshlrev_b32_e32 v0, 1, v0
	v_lshl_add_u64 v[64:65], s[0:1], 0, v[0:1]
	v_lshl_add_u32 v66, v125, 2, v127
	v_readlane_b32 s2, v255, 60
	s_mov_b32 s3, 0x4000
	s_andn2_b32 s3, s3, s2
	v_readlane_b32 s2, v255, 9
	s_lshr_b32 s3, s3, s2
	s_and_b32 s3, s3, 1
	s_mul_i32 s3, s3, 0x1b240000
	s_add_u32 s22, s22, s3
	s_addc_u32 s23, s23, 0
	v_lshl_add_u64 v[62:63], s[22:23], 0, v[0:1]
	v_and_b32_e32 v0, 15, v125
	v_cmp_ne_u32_e32 vcc, 0, v0
	v_add_u32_e32 v0, 4, v66
	v_ashrrev_i32_e32 v67, 31, v66
	v_and_b32_e32 v58, 60, v0
	v_lshlrev_b64 v[70:71], 1, v[66:67]
	v_cmp_eq_u32_e64 s[4:5], 0, v58
	v_cndmask_b32_e64 v58, 0, -1, vcc
	v_lshl_add_u64 v[68:69], v[64:65], 0, v[70:71]
	v_mov_b32_e32 v59, v58
	v_lshl_add_u64 v[58:59], v[58:59], 1, v[68:69]
	v_lshrrev_b32_e32 v58, 16, v152
	v_cndmask_b32_e64 v74, 0, 1.0, vcc
	v_mov_b32_e32 v80, v153
	v_mov_b32_e32 v81, v154
	v_lshl_add_u32 v67, v125, 3, v129
	v_lshl_add_u64 v[62:63], v[62:63], 0, v[70:71]
	v_add_u32_e32 v70, 16, v66
	v_add_u32_e32 v71, 20, v66
	s_mov_b64 s[0:1], 0x1e0
	s_nop 0
	v_lshlrev_b32_e32 v58, 16, v58
	v_mul_f32_e32 v73, v74, v58
	v_cndmask_b32_e64 v58, v0, v66, s[4:5]
	v_ashrrev_i32_e32 v59, 31, v58
	v_lshl_add_u64 v[58:59], v[58:59], 1, v[64:65]
	v_and_b32_e32 v0, 0xffff, v155
	v_cndmask_b32_e64 v58, 1.0, 0, s[4:5]
	s_nop 0
	v_and_b32_e32 v82, 0xffff0000, v80
	v_mov_b32_e32 v72, v82
	v_pk_mul_f32 v[72:73], v[122:123], v[72:73]
	v_lshlrev_b32_e32 v83, 16, v81
	v_and_b32_e32 v81, 0xffff0000, v81
	v_mov_b32_e32 v76, v81
	s_nop 0
	v_lshlrev_b32_e32 v0, 16, v0
	v_mul_f32_e32 v77, v58, v0
	ds_read2_b64 v[58:61], v67 offset1:4
	v_lshlrev_b32_e32 v0, 16, v80
	v_pk_fma_f32 v[72:73], v[122:123], v[0:1], v[72:73] op_sel:[0,0,1] op_sel_hi:[1,0,0]
	v_mov_b32_e32 v80, v83
	v_pk_fma_f32 v[72:73], v[126:127], v[82:83], v[72:73] op_sel_hi:[0,1,1]
	s_waitcnt lgkmcnt(0)
	v_lshlrev_b32_e32 v78, 16, v58
	v_and_b32_e32 v79, 0xffff0000, v58
	v_pk_fma_f32 v[78:79], v[128:129], v[78:79], v[118:119] op_sel_hi:[0,1,1]
	v_pk_add_f32 v[72:73], v[124:125], v[72:73] op_sel_hi:[0,1]
	v_pk_mul_f32 v[72:73], v[72:73], v[78:79]
	v_mov_b32_e32 v0, v123
	v_pk_mul_f32 v[78:79], v[122:123], v[80:81] op_sel_hi:[0,1]
	v_pk_fma_f32 v[78:79], v[0:1], v[82:83], v[78:79] op_sel_hi:[0,1,1]
	v_lshlrev_b32_e32 v58, 16, v59
	v_and_b32_e32 v59, 0xffff0000, v59
	v_pk_fma_f32 v[76:77], v[126:127], v[76:77], v[78:79] op_sel_hi:[0,1,1]
	v_pk_add_f32 v[76:77], v[124:125], v[76:77] op_sel_hi:[0,1]
	v_pk_fma_f32 v[58:59], v[128:129], v[58:59], v[120:121] op_sel_hi:[0,1,1]
	v_pk_mul_f32 v[58:59], v[58:59], v[76:77]
	v_cvt_pk_bf16_f32 v72, v72, v73
	v_cvt_pk_bf16_f32 v73, v58, v59
	v_and_b32_e32 v58, 60, v70
	v_cmp_ne_u32_e64 s[4:5], 0, v58
	v_and_b32_e32 v58, 60, v71
	v_cmp_eq_u32_e64 s[6:7], 0, v58
	v_subbrev_co_u32_e64 v58, s[8:9], 0, v70, s[4:5]
	v_ashrrev_i32_e32 v59, 31, v58
	global_store_dwordx2 v[62:63], v[72:73], off
	v_lshl_add_u64 v[58:59], v[58:59], 1, v[64:65]
	v_lshrrev_b32_e32 v58, 16, v156
	v_cndmask_b32_e64 v70, v71, v70, s[6:7]
	v_ashrrev_i32_e32 v71, 31, v70
	v_lshl_add_u64 v[70:71], v[70:71], 1, v[64:65]
	v_mov_b32_e32 v76, v157
	v_mov_b32_e32 v77, v158
	v_cndmask_b32_e64 v59, 0, 1.0, s[4:5]
	v_lshlrev_b32_e32 v72, 16, v60
	v_and_b32_e32 v73, 0xffff0000, v60
	v_pk_fma_f32 v[72:73], v[128:129], v[72:73], v[114:115] op_sel_hi:[0,1,1]
	v_lshlrev_b32_e32 v60, 16, v61
	v_and_b32_e32 v61, 0xffff0000, v61
	v_pk_fma_f32 v[60:61], v[128:129], v[60:61], v[116:117] op_sel_hi:[0,1,1]
	s_nop 0
	v_lshlrev_b32_e32 v58, 16, v58
	v_mul_f32_e32 v59, v59, v58
	v_and_b32_e32 v58, 0xffff, v159
	v_cndmask_b32_e64 v70, 1.0, 0, s[6:7]
	s_nop 0
	v_and_b32_e32 v78, 0xffff0000, v76
	v_lshlrev_b32_e32 v79, 16, v77
	v_and_b32_e32 v77, 0xffff0000, v77
	s_nop 0
	v_lshlrev_b32_e32 v58, 16, v58
	v_mul_f32_e32 v71, v70, v58
	v_mov_b32_e32 v58, v78
	v_lshlrev_b32_e32 v70, 16, v76
	v_pk_mul_f32 v[58:59], v[122:123], v[58:59]
	v_mov_b32_e32 v76, v79
	v_pk_fma_f32 v[58:59], v[122:123], v[70:71], v[58:59] op_sel:[0,0,1] op_sel_hi:[1,0,0]
	v_mov_b32_e32 v70, v77
	v_pk_fma_f32 v[58:59], v[126:127], v[78:79], v[58:59] op_sel_hi:[0,1,1]
	v_pk_add_f32 v[58:59], v[124:125], v[58:59] op_sel_hi:[0,1]
	v_pk_mul_f32 v[58:59], v[58:59], v[72:73]
	v_pk_mul_f32 v[72:73], v[122:123], v[76:77] op_sel_hi:[0,1]
	v_pk_fma_f32 v[72:73], v[0:1], v[78:79], v[72:73] op_sel_hi:[0,1,1]
	v_pk_fma_f32 v[70:71], v[126:127], v[70:71], v[72:73] op_sel_hi:[0,1,1]
	v_pk_add_f32 v[70:71], v[124:125], v[70:71] op_sel_hi:[0,1]
	v_pk_mul_f32 v[60:61], v[60:61], v[70:71]
	v_cvt_pk_bf16_f32 v58, v58, v59
	v_cvt_pk_bf16_f32 v59, v60, v61
	v_add_u32_e32 v60, 32, v66
	global_store_dwordx2 v[62:63], v[58:59], off offset:32
	v_and_b32_e32 v58, 60, v60
	v_add_u32_e32 v61, 36, v66
	v_cmp_ne_u32_e64 s[4:5], 0, v58
	v_and_b32_e32 v58, 60, v61
	v_cmp_eq_u32_e64 s[6:7], 0, v58
	v_subbrev_co_u32_e64 v58, s[8:9], 0, v60, s[4:5]
	v_ashrrev_i32_e32 v59, 31, v58
	v_lshl_add_u64 v[58:59], v[58:59], 1, v[64:65]
	v_lshrrev_b32_e32 v58, 16, v160
	s_nop 0
	v_mov_b32_e32 v78, v161
	v_mov_b32_e32 v79, v162
	v_cndmask_b32_e64 v59, 0, 1.0, s[4:5]
	s_nop 0
	v_lshlrev_b32_e32 v58, 16, v58
	v_mul_f32_e32 v73, v59, v58
	v_cndmask_b32_e64 v58, v61, v60, s[6:7]
	v_ashrrev_i32_e32 v59, 31, v58
	v_lshl_add_u64 v[58:59], v[58:59], 1, v[64:65]
	v_and_b32_e32 v58, 0xffff, v163
	v_cndmask_b32_e64 v59, 1.0, 0, s[6:7]
	s_nop 0
	v_and_b32_e32 v80, 0xffff0000, v78
	v_mov_b32_e32 v72, v80
	v_lshlrev_b32_e32 v70, 16, v78
	v_pk_mul_f32 v[72:73], v[122:123], v[72:73]
	v_lshlrev_b32_e32 v81, 16, v79
	v_and_b32_e32 v79, 0xffff0000, v79
	v_mov_b32_e32 v78, v81
	s_nop 0
	v_lshlrev_b32_e32 v58, 16, v58
	v_mul_f32_e32 v71, v59, v58
	ds_read2_b64 v[58:61], v67 offset0:8 offset1:12
	v_pk_fma_f32 v[72:73], v[122:123], v[70:71], v[72:73] op_sel:[0,0,1] op_sel_hi:[1,0,0]
	v_mov_b32_e32 v70, v79
	v_pk_fma_f32 v[72:73], v[126:127], v[80:81], v[72:73] op_sel_hi:[0,1,1]
	v_pk_add_f32 v[72:73], v[124:125], v[72:73] op_sel_hi:[0,1]
	s_waitcnt lgkmcnt(0)
; DI float bf2f(bfu v) { return __uint_as_float(((unsigned)v) << 16); }
; DI unsigned pack2(float a, float b) { f32x2_t v = {a, b}; bf16x2_t r = __builtin_convertvector(v, bf16x2_t); return __builtin_bit_cast(unsigned, r); }
; DI float lo16(unsigned u) { return __uint_as_float(u << 16); }
; DI float hi16(unsigned u) { return __uint_as_float(u & 0xffff0000u); }
; template <int L>
; DI void hyena_job(const PX& p, int l, int c, unsigned char* smem) {
;     ...
; #pragma unroll
;     for (int m = 0; m < TPW; m++) {
;       const int t0 = 16 * (w * TPW + m) + 4 * kq_o;
;       const bfu* zr = zx2 + b * L;
;       const uint2 mid = *(const uint2*)(zr + t0);
;       const bool lv = (t0 % RL != 0), rv = ((t0 + 4) % RL != 0);
;       const float lft = bf2f(zr[lv ? t0 - 1 : t0]) * (lv ? 1.f : 0.f);
;       const float rgt = bf2f(zr[rv ? t0 + 4 : t0]) * (rv ? 1.f : 0.f);
;       float z[6];
;       z[0] = lft; z[5] = rgt; z[1] = lo16(mid.x); z[2] = hi16(mid.x); z[3] = lo16(mid.y); z[4] = hi16(mid.y);
;       const uint2 vu = *(const uint2*)(U + b * USTR + t0);
;       const float vv[4] = {lo16(vu.x), hi16(vu.x), lo16(vu.y), hi16(vu.y)};
;       float y2[4];
; #pragma unroll
;       for (int r = 0; r < 4; r++) {
;         const float x2 = w2[0] * z[r] + w2[1] * z[r + 1] + w2[2] * z[r + 2] + w2[3];
;         y2[r] = x2 * (acc[m][r] + bias1 * vv[r]);
;       }
;       uint2 o2; o2.x = pack2(y2[0], y2[1]); o2.y = pack2(y2[2], y2[3]);
;       *(uint2*)(yrow + b * L + t0) = o2;
;     }
	v_lshlrev_b32_e32 v76, 16, v58
	v_and_b32_e32 v77, 0xffff0000, v58
	v_pk_fma_f32 v[54:55], v[128:129], v[76:77], v[54:55] op_sel_hi:[0,1,1]
	v_pk_mul_f32 v[54:55], v[72:73], v[54:55]
	v_pk_mul_f32 v[72:73], v[122:123], v[78:79] op_sel_hi:[0,1]
	v_pk_fma_f32 v[72:73], v[0:1], v[80:81], v[72:73] op_sel_hi:[0,1,1]
	v_lshlrev_b32_e32 v58, 16, v59
	v_and_b32_e32 v59, 0xffff0000, v59
	v_pk_fma_f32 v[70:71], v[126:127], v[70:71], v[72:73] op_sel_hi:[0,1,1]
	v_pk_add_f32 v[70:71], v[124:125], v[70:71] op_sel_hi:[0,1]
	v_pk_fma_f32 v[56:57], v[128:129], v[58:59], v[56:57] op_sel_hi:[0,1,1]
	v_pk_mul_f32 v[56:57], v[56:57], v[70:71]
	v_cvt_pk_bf16_f32 v54, v54, v55
	v_cvt_pk_bf16_f32 v55, v56, v57
	v_add_u32_e32 v56, 48, v66
	global_store_dwordx2 v[62:63], v[54:55], off offset:64
	v_and_b32_e32 v54, 60, v56
	v_add_u32_e32 v58, 52, v66
	v_cmp_ne_u32_e64 s[4:5], 0, v54
	v_and_b32_e32 v54, 60, v58
	v_cmp_eq_u32_e64 s[6:7], 0, v54
	v_subbrev_co_u32_e64 v54, s[8:9], 0, v56, s[4:5]
	v_ashrrev_i32_e32 v55, 31, v54
	v_lshl_add_u64 v[54:55], v[54:55], 1, v[64:65]
	v_lshrrev_b32_e32 v54, 16, v164
	v_cndmask_b32_e64 v55, 0, 1.0, s[4:5]
	v_lshlrev_b32_e32 v70, 16, v60
	v_and_b32_e32 v71, 0xffff0000, v60
	v_and_b32_e32 v59, 0xffff0000, v61
	v_pk_fma_f32 v[50:51], v[128:129], v[70:71], v[50:51] op_sel_hi:[0,1,1]
	s_nop 0
	v_lshlrev_b32_e32 v54, 16, v54
	v_mul_f32_e32 v57, v55, v54
	v_cndmask_b32_e64 v54, v58, v56, s[6:7]
	v_ashrrev_i32_e32 v55, 31, v54
	v_lshl_add_u64 v[54:55], v[54:55], 1, v[64:65]
	v_and_b32_e32 v54, 0xffff, v167
	v_lshlrev_b32_e32 v58, 16, v61
	v_mov_b32_e32 v60, v165
	v_mov_b32_e32 v61, v166
	v_cndmask_b32_e64 v55, 1.0, 0, s[6:7]
	v_pk_fma_f32 v[52:53], v[128:129], v[58:59], v[52:53] op_sel_hi:[0,1,1]
	s_nop 0
	v_lshlrev_b32_e32 v54, 16, v54
	v_mul_f32_e32 v55, v55, v54
	s_nop 0
	v_and_b32_e32 v72, 0xffff0000, v60
	v_mov_b32_e32 v56, v72
	v_lshlrev_b32_e32 v54, 16, v60
	v_pk_mul_f32 v[56:57], v[122:123], v[56:57]
	v_lshlrev_b32_e32 v73, 16, v61
	v_pk_fma_f32 v[56:57], v[122:123], v[54:55], v[56:57] op_sel:[0,0,1] op_sel_hi:[1,0,0]
	v_and_b32_e32 v61, 0xffff0000, v61
	v_pk_fma_f32 v[56:57], v[126:127], v[72:73], v[56:57] op_sel_hi:[0,1,1]
	v_mov_b32_e32 v60, v73
	v_pk_add_f32 v[56:57], v[124:125], v[56:57] op_sel_hi:[0,1]
	v_pk_mul_f32 v[50:51], v[56:57], v[50:51]
	v_pk_mul_f32 v[56:57], v[122:123], v[60:61] op_sel_hi:[0,1]
	v_pk_fma_f32 v[56:57], v[0:1], v[72:73], v[56:57] op_sel_hi:[0,1,1]
	v_mov_b32_e32 v54, v61
	v_pk_fma_f32 v[54:55], v[126:127], v[54:55], v[56:57] op_sel_hi:[0,1,1]
	v_pk_add_f32 v[54:55], v[124:125], v[54:55] op_sel_hi:[0,1]
	v_pk_mul_f32 v[52:53], v[52:53], v[54:55]
	v_cvt_pk_bf16_f32 v50, v50, v51
	v_cvt_pk_bf16_f32 v51, v52, v53
	v_add_u32_e32 v53, 0x44, v66
	global_store_dwordx2 v[62:63], v[50:51], off offset:96
	v_add_u32_e32 v52, 64, v66
	v_and_b32_e32 v50, 60, v53
	v_cmp_eq_u32_e64 s[4:5], 0, v50
	v_subbrev_co_u32_e64 v50, s[6:7], 0, v52, vcc
	v_ashrrev_i32_e32 v51, 31, v50
	v_lshl_add_u64 v[50:51], v[50:51], 1, v[64:65]
	v_lshrrev_b32_e32 v50, 16, v168
	s_nop 0
	v_mov_b32_e32 v60, v169
	v_mov_b32_e32 v61, v170
	s_nop 0
	v_lshlrev_b32_e32 v50, 16, v50
	v_mul_f32_e32 v55, v74, v50
	v_cndmask_b32_e64 v50, v53, v52, s[4:5]
	v_ashrrev_i32_e32 v51, 31, v50
	v_lshl_add_u64 v[50:51], v[50:51], 1, v[64:65]
	v_and_b32_e32 v50, 0xffff, v171
	v_cndmask_b32_e64 v51, 1.0, 0, s[4:5]
	s_nop 0
	v_and_b32_e32 v70, 0xffff0000, v60
	v_mov_b32_e32 v54, v70
	v_lshlrev_b32_e32 v56, 16, v60
	v_pk_mul_f32 v[54:55], v[122:123], v[54:55]
	v_lshlrev_b32_e32 v71, 16, v61
	v_and_b32_e32 v61, 0xffff0000, v61
	v_mov_b32_e32 v60, v71
	s_nop 0
	v_lshlrev_b32_e32 v50, 16, v50
	v_mul_f32_e32 v57, v51, v50
	ds_read2_b64 v[50:53], v67 offset0:16 offset1:20
	v_pk_fma_f32 v[54:55], v[122:123], v[56:57], v[54:55] op_sel:[0,0,1] op_sel_hi:[1,0,0]
	v_mov_b32_e32 v56, v61
	v_pk_fma_f32 v[54:55], v[126:127], v[70:71], v[54:55] op_sel_hi:[0,1,1]
	v_pk_add_f32 v[54:55], v[124:125], v[54:55] op_sel_hi:[0,1]
	s_waitcnt lgkmcnt(0)
	v_lshlrev_b32_e32 v58, 16, v50
	v_and_b32_e32 v59, 0xffff0000, v50
	v_pk_fma_f32 v[46:47], v[128:129], v[58:59], v[46:47] op_sel_hi:[0,1,1]
	v_pk_mul_f32 v[46:47], v[54:55], v[46:47]
	v_pk_mul_f32 v[54:55], v[122:123], v[60:61] op_sel_hi:[0,1]
	v_pk_fma_f32 v[54:55], v[0:1], v[70:71], v[54:55] op_sel_hi:[0,1,1]
	v_lshlrev_b32_e32 v50, 16, v51
	v_and_b32_e32 v51, 0xffff0000, v51
	v_pk_fma_f32 v[54:55], v[126:127], v[56:57], v[54:55] op_sel_hi:[0,1,1]
	v_pk_add_f32 v[54:55], v[124:125], v[54:55] op_sel_hi:[0,1]
	v_pk_fma_f32 v[48:49], v[128:129], v[50:51], v[48:49] op_sel_hi:[0,1,1]
	v_pk_mul_f32 v[48:49], v[48:49], v[54:55]
	v_cvt_pk_bf16_f32 v46, v46, v47
	v_cvt_pk_bf16_f32 v47, v48, v49
	v_add_u32_e32 v48, 0x50, v66
	global_store_dwordx2 v[62:63], v[46:47], off offset:128
	v_and_b32_e32 v46, 60, v48
	v_add_u32_e32 v49, 0x54, v66
	v_cmp_ne_u32_e64 s[4:5], 0, v46
	v_and_b32_e32 v46, 60, v49
	v_cmp_eq_u32_e64 s[6:7], 0, v46
	v_subbrev_co_u32_e64 v46, s[8:9], 0, v48, s[4:5]
	v_ashrrev_i32_e32 v47, 31, v46
	v_lshl_add_u64 v[46:47], v[46:47], 1, v[64:65]
	v_lshrrev_b32_e32 v46, 16, v172
	v_cndmask_b32_e64 v48, v49, v48, s[6:7]
	v_ashrrev_i32_e32 v49, 31, v48
	v_lshl_add_u64 v[48:49], v[48:49], 1, v[64:65]
	v_mov_b32_e32 v54, v173
	v_mov_b32_e32 v55, v174
	v_cndmask_b32_e64 v47, 0, 1.0, s[4:5]
	v_lshlrev_b32_e32 v50, 16, v52
	v_and_b32_e32 v51, 0xffff0000, v52
	v_pk_fma_f32 v[42:43], v[128:129], v[50:51], v[42:43] op_sel_hi:[0,1,1]
	v_lshlrev_b32_e32 v52, 16, v53
	v_and_b32_e32 v53, 0xffff0000, v53
	v_pk_fma_f32 v[44:45], v[128:129], v[52:53], v[44:45] op_sel_hi:[0,1,1]
	v_mov_b32_e32 v52, v177
	v_mov_b32_e32 v53, v178
	s_nop 0
; DI float bf2f(bfu v) { return __uint_as_float(((unsigned)v) << 16); }
; DI unsigned pack2(float a, float b) { f32x2_t v = {a, b}; bf16x2_t r = __builtin_convertvector(v, bf16x2_t); return __builtin_bit_cast(unsigned, r); }
; DI float lo16(unsigned u) { return __uint_as_float(u << 16); }
; DI float hi16(unsigned u) { return __uint_as_float(u & 0xffff0000u); }
; template <int L>
; DI void hyena_job(const PX& p, int l, int c, unsigned char* smem) {
;     ...
; #pragma unroll
;     for (int m = 0; m < TPW; m++) {
;       const int t0 = 16 * (w * TPW + m) + 4 * kq_o;
;       const bfu* zr = zx2 + b * L;
;       const uint2 mid = *(const uint2*)(zr + t0);
;       const bool lv = (t0 % RL != 0), rv = ((t0 + 4) % RL != 0);
;       const float lft = bf2f(zr[lv ? t0 - 1 : t0]) * (lv ? 1.f : 0.f);
;       const float rgt = bf2f(zr[rv ? t0 + 4 : t0]) * (rv ? 1.f : 0.f);
;       float z[6];
;       z[0] = lft; z[5] = rgt; z[1] = lo16(mid.x); z[2] = hi16(mid.x); z[3] = lo16(mid.y); z[4] = hi16(mid.y);
;       const uint2 vu = *(const uint2*)(U + b * USTR + t0);
;       const float vv[4] = {lo16(vu.x), hi16(vu.x), lo16(vu.y), hi16(vu.y)};
;       float y2[4];
; #pragma unroll
;       for (int r = 0; r < 4; r++) {
;         const float x2 = w2[0] * z[r] + w2[1] * z[r + 1] + w2[2] * z[r + 2] + w2[3];
;         y2[r] = x2 * (acc[m][r] + bias1 * vv[r]);
;       }
;       uint2 o2; o2.x = pack2(y2[0], y2[1]); o2.y = pack2(y2[2], y2[3]);
;       *(uint2*)(yrow + b * L + t0) = o2;
;     }
	v_lshlrev_b32_e32 v46, 16, v46
	v_mul_f32_e32 v47, v47, v46
	v_and_b32_e32 v46, 0xffff, v175
	v_cndmask_b32_e64 v48, 1.0, 0, s[6:7]
	s_nop 0
	v_and_b32_e32 v56, 0xffff0000, v54
	v_lshlrev_b32_e32 v57, 16, v55
	v_and_b32_e32 v55, 0xffff0000, v55
	s_nop 0
	v_lshlrev_b32_e32 v46, 16, v46
	v_mul_f32_e32 v49, v48, v46
	v_mov_b32_e32 v46, v56
	v_lshlrev_b32_e32 v48, 16, v54
	v_pk_mul_f32 v[46:47], v[122:123], v[46:47]
	v_mov_b32_e32 v54, v57
	v_pk_fma_f32 v[46:47], v[122:123], v[48:49], v[46:47] op_sel:[0,0,1] op_sel_hi:[1,0,0]
	v_mov_b32_e32 v48, v55
	v_pk_fma_f32 v[46:47], v[126:127], v[56:57], v[46:47] op_sel_hi:[0,1,1]
	v_pk_add_f32 v[46:47], v[124:125], v[46:47] op_sel_hi:[0,1]
	v_pk_mul_f32 v[42:43], v[46:47], v[42:43]
	v_pk_mul_f32 v[46:47], v[122:123], v[54:55] op_sel_hi:[0,1]
	v_pk_fma_f32 v[46:47], v[0:1], v[56:57], v[46:47] op_sel_hi:[0,1,1]
	v_pk_fma_f32 v[46:47], v[126:127], v[48:49], v[46:47] op_sel_hi:[0,1,1]
	v_pk_add_f32 v[46:47], v[124:125], v[46:47] op_sel_hi:[0,1]
	v_pk_mul_f32 v[44:45], v[44:45], v[46:47]
	v_cvt_pk_bf16_f32 v42, v42, v43
	v_cvt_pk_bf16_f32 v43, v44, v45
	v_add_u32_e32 v44, 0x60, v66
	global_store_dwordx2 v[62:63], v[42:43], off offset:160
	v_and_b32_e32 v42, 60, v44
	v_add_u32_e32 v45, 0x64, v66
	v_cmp_ne_u32_e64 s[4:5], 0, v42
	v_and_b32_e32 v42, 60, v45
	v_cmp_eq_u32_e64 s[6:7], 0, v42
	v_subbrev_co_u32_e64 v42, s[8:9], 0, v44, s[4:5]
	v_ashrrev_i32_e32 v43, 31, v42
	v_lshl_add_u64 v[42:43], v[42:43], 1, v[64:65]
	v_lshrrev_b32_e32 v42, 16, v176
	v_cndmask_b32_e64 v43, 0, 1.0, s[4:5]
	v_and_b32_e32 v54, 0xffff0000, v52
	v_mov_b32_e32 v48, v54
	v_lshlrev_b32_e32 v46, 16, v52
	v_lshlrev_b32_e32 v55, 16, v53
	v_and_b32_e32 v53, 0xffff0000, v53
	v_mov_b32_e32 v52, v55
	s_nop 0
	v_lshlrev_b32_e32 v42, 16, v42
	v_mul_f32_e32 v49, v43, v42
	v_cndmask_b32_e64 v42, v45, v44, s[6:7]
	v_ashrrev_i32_e32 v43, 31, v42
	v_lshl_add_u64 v[42:43], v[42:43], 1, v[64:65]
	v_and_b32_e32 v42, 0xffff, v179
	v_cndmask_b32_e64 v43, 1.0, 0, s[6:7]
	v_pk_mul_f32 v[48:49], v[122:123], v[48:49]
	s_nop 0
	v_lshlrev_b32_e32 v42, 16, v42
	v_mul_f32_e32 v47, v43, v42
	ds_read2_b64 v[42:45], v67 offset0:24 offset1:28
	v_pk_fma_f32 v[48:49], v[122:123], v[46:47], v[48:49] op_sel:[0,0,1] op_sel_hi:[1,0,0]
	v_mov_b32_e32 v46, v53
	v_pk_fma_f32 v[48:49], v[126:127], v[54:55], v[48:49] op_sel_hi:[0,1,1]
	v_pk_add_f32 v[48:49], v[124:125], v[48:49] op_sel_hi:[0,1]
	s_waitcnt lgkmcnt(0)
	v_lshlrev_b32_e32 v50, 16, v42
	v_and_b32_e32 v51, 0xffff0000, v42
	v_pk_fma_f32 v[38:39], v[128:129], v[50:51], v[38:39] op_sel_hi:[0,1,1]
	v_pk_mul_f32 v[38:39], v[48:49], v[38:39]
	v_pk_mul_f32 v[48:49], v[122:123], v[52:53] op_sel_hi:[0,1]
	v_pk_fma_f32 v[48:49], v[0:1], v[54:55], v[48:49] op_sel_hi:[0,1,1]
	v_lshlrev_b32_e32 v42, 16, v43
	v_and_b32_e32 v43, 0xffff0000, v43
	v_pk_fma_f32 v[46:47], v[126:127], v[46:47], v[48:49] op_sel_hi:[0,1,1]
	v_pk_add_f32 v[46:47], v[124:125], v[46:47] op_sel_hi:[0,1]
	v_pk_fma_f32 v[40:41], v[128:129], v[42:43], v[40:41] op_sel_hi:[0,1,1]
	v_pk_mul_f32 v[40:41], v[40:41], v[46:47]
	v_cvt_pk_bf16_f32 v38, v38, v39
	v_cvt_pk_bf16_f32 v39, v40, v41
	v_add_u32_e32 v40, 0x70, v66
	global_store_dwordx2 v[62:63], v[38:39], off offset:192
	v_and_b32_e32 v38, 60, v40
	v_add_u32_e32 v42, 0x74, v66
	v_cmp_ne_u32_e64 s[4:5], 0, v38
	v_and_b32_e32 v38, 60, v42
	v_cmp_eq_u32_e64 s[6:7], 0, v38
	v_subbrev_co_u32_e64 v38, s[8:9], 0, v40, s[4:5]
	v_ashrrev_i32_e32 v39, 31, v38
	v_lshl_add_u64 v[38:39], v[38:39], 1, v[64:65]
	v_lshrrev_b32_e32 v38, 16, v180
	v_cndmask_b32_e64 v39, 0, 1.0, s[4:5]
	v_lshlrev_b32_e32 v46, 16, v44
	v_and_b32_e32 v47, 0xffff0000, v44
	v_and_b32_e32 v43, 0xffff0000, v45
	v_pk_fma_f32 v[34:35], v[128:129], v[46:47], v[34:35] op_sel_hi:[0,1,1]
	s_nop 0
	v_lshlrev_b32_e32 v38, 16, v38
	v_mul_f32_e32 v41, v39, v38
	v_cndmask_b32_e64 v38, v42, v40, s[6:7]
	v_ashrrev_i32_e32 v39, 31, v38
	v_lshl_add_u64 v[38:39], v[38:39], 1, v[64:65]
	v_and_b32_e32 v38, 0xffff, v183
	v_lshlrev_b32_e32 v42, 16, v45
	v_mov_b32_e32 v44, v181
	v_mov_b32_e32 v45, v182
	v_cndmask_b32_e64 v39, 1.0, 0, s[6:7]
	v_pk_fma_f32 v[36:37], v[128:129], v[42:43], v[36:37] op_sel_hi:[0,1,1]
	s_nop 0
	v_lshlrev_b32_e32 v38, 16, v38
	v_mul_f32_e32 v39, v39, v38
	s_nop 0
	v_and_b32_e32 v48, 0xffff0000, v44
	v_mov_b32_e32 v40, v48
	v_lshlrev_b32_e32 v38, 16, v44
	v_pk_mul_f32 v[40:41], v[122:123], v[40:41]
	v_lshlrev_b32_e32 v49, 16, v45
	v_pk_fma_f32 v[40:41], v[122:123], v[38:39], v[40:41] op_sel:[0,0,1] op_sel_hi:[1,0,0]
	v_and_b32_e32 v45, 0xffff0000, v45
	v_pk_fma_f32 v[40:41], v[126:127], v[48:49], v[40:41] op_sel_hi:[0,1,1]
	v_mov_b32_e32 v44, v49
	v_pk_add_f32 v[40:41], v[124:125], v[40:41] op_sel_hi:[0,1]
	v_pk_mul_f32 v[34:35], v[40:41], v[34:35]
	v_pk_mul_f32 v[40:41], v[122:123], v[44:45] op_sel_hi:[0,1]
	v_pk_fma_f32 v[40:41], v[0:1], v[48:49], v[40:41] op_sel_hi:[0,1,1]
	v_mov_b32_e32 v38, v45
	v_pk_fma_f32 v[38:39], v[126:127], v[38:39], v[40:41] op_sel_hi:[0,1,1]
	v_pk_add_f32 v[38:39], v[124:125], v[38:39] op_sel_hi:[0,1]
	v_pk_mul_f32 v[36:37], v[36:37], v[38:39]
	v_cvt_pk_bf16_f32 v34, v34, v35
	v_cvt_pk_bf16_f32 v35, v36, v37
	v_add_u32_e32 v37, 0x84, v66
	global_store_dwordx2 v[62:63], v[34:35], off offset:224
	v_add_u32_e32 v36, 0x80, v66
	v_and_b32_e32 v34, 60, v37
	v_cmp_eq_u32_e64 s[4:5], 0, v34
	v_subbrev_co_u32_e64 v34, s[6:7], 0, v36, vcc
	v_ashrrev_i32_e32 v35, 31, v34
	v_lshl_add_u64 v[34:35], v[34:35], 1, v[64:65]
	v_lshrrev_b32_e32 v34, 16, v216
	s_nop 0
	v_mov_b32_e32 v44, v217
	v_mov_b32_e32 v45, v218
	s_nop 0
	v_lshlrev_b32_e32 v34, 16, v34
	v_mul_f32_e32 v39, v74, v34
	v_cndmask_b32_e64 v34, v37, v36, s[4:5]
	v_ashrrev_i32_e32 v35, 31, v34
	v_lshl_add_u64 v[34:35], v[34:35], 1, v[64:65]
	v_and_b32_e32 v34, 0xffff, v219
	v_cndmask_b32_e64 v35, 1.0, 0, s[4:5]
	s_nop 0
	v_and_b32_e32 v46, 0xffff0000, v44
	v_mov_b32_e32 v38, v46
	v_lshlrev_b32_e32 v40, 16, v44
	v_pk_mul_f32 v[38:39], v[122:123], v[38:39]
	v_lshlrev_b32_e32 v47, 16, v45
	v_and_b32_e32 v45, 0xffff0000, v45
	v_mov_b32_e32 v44, v47
	s_nop 0
	v_lshlrev_b32_e32 v34, 16, v34
	v_mul_f32_e32 v41, v35, v34
	ds_read2_b64 v[34:37], v67 offset0:32 offset1:36
	v_pk_fma_f32 v[38:39], v[122:123], v[40:41], v[38:39] op_sel:[0,0,1] op_sel_hi:[1,0,0]
	v_mov_b32_e32 v40, v45
	v_pk_fma_f32 v[38:39], v[126:127], v[46:47], v[38:39] op_sel_hi:[0,1,1]
	v_pk_add_f32 v[38:39], v[124:125], v[38:39] op_sel_hi:[0,1]
	s_waitcnt lgkmcnt(0)
; DI float bf2f(bfu v) { return __uint_as_float(((unsigned)v) << 16); }
; DI unsigned pack2(float a, float b) { f32x2_t v = {a, b}; bf16x2_t r = __builtin_convertvector(v, bf16x2_t); return __builtin_bit_cast(unsigned, r); }
; DI float lo16(unsigned u) { return __uint_as_float(u << 16); }
; DI float hi16(unsigned u) { return __uint_as_float(u & 0xffff0000u); }
; template <int L>
; DI void hyena_job(const PX& p, int l, int c, unsigned char* smem) {
;     ...
; #pragma unroll
;     for (int m = 0; m < TPW; m++) {
;       const int t0 = 16 * (w * TPW + m) + 4 * kq_o;
;       const bfu* zr = zx2 + b * L;
;       const uint2 mid = *(const uint2*)(zr + t0);
;       const bool lv = (t0 % RL != 0), rv = ((t0 + 4) % RL != 0);
;       const float lft = bf2f(zr[lv ? t0 - 1 : t0]) * (lv ? 1.f : 0.f);
;       const float rgt = bf2f(zr[rv ? t0 + 4 : t0]) * (rv ? 1.f : 0.f);
;       float z[6];
;       z[0] = lft; z[5] = rgt; z[1] = lo16(mid.x); z[2] = hi16(mid.x); z[3] = lo16(mid.y); z[4] = hi16(mid.y);
;       const uint2 vu = *(const uint2*)(U + b * USTR + t0);
;       const float vv[4] = {lo16(vu.x), hi16(vu.x), lo16(vu.y), hi16(vu.y)};
;       float y2[4];
; #pragma unroll
;       for (int r = 0; r < 4; r++) {
;         const float x2 = w2[0] * z[r] + w2[1] * z[r + 1] + w2[2] * z[r + 2] + w2[3];
;         y2[r] = x2 * (acc[m][r] + bias1 * vv[r]);
;       }
;       uint2 o2; o2.x = pack2(y2[0], y2[1]); o2.y = pack2(y2[2], y2[3]);
;       *(uint2*)(yrow + b * L + t0) = o2;
;     }
	v_lshlrev_b32_e32 v42, 16, v34
	v_and_b32_e32 v43, 0xffff0000, v34
	v_pk_fma_f32 v[30:31], v[128:129], v[42:43], v[30:31] op_sel_hi:[0,1,1]
	v_pk_mul_f32 v[30:31], v[38:39], v[30:31]
	v_pk_mul_f32 v[38:39], v[122:123], v[44:45] op_sel_hi:[0,1]
	v_pk_fma_f32 v[38:39], v[0:1], v[46:47], v[38:39] op_sel_hi:[0,1,1]
	v_lshlrev_b32_e32 v34, 16, v35
	v_and_b32_e32 v35, 0xffff0000, v35
	v_pk_fma_f32 v[38:39], v[126:127], v[40:41], v[38:39] op_sel_hi:[0,1,1]
	v_pk_add_f32 v[38:39], v[124:125], v[38:39] op_sel_hi:[0,1]
	v_pk_fma_f32 v[32:33], v[128:129], v[34:35], v[32:33] op_sel_hi:[0,1,1]
	v_pk_mul_f32 v[32:33], v[32:33], v[38:39]
	v_cvt_pk_bf16_f32 v30, v30, v31
	v_cvt_pk_bf16_f32 v31, v32, v33
	v_add_u32_e32 v32, 0x90, v66
	global_store_dwordx2 v[62:63], v[30:31], off offset:256
	v_and_b32_e32 v30, 60, v32
	v_add_u32_e32 v33, 0x94, v66
	v_cmp_ne_u32_e64 s[4:5], 0, v30
	v_and_b32_e32 v30, 60, v33
	v_cmp_eq_u32_e64 s[6:7], 0, v30
	v_subbrev_co_u32_e64 v30, s[8:9], 0, v32, s[4:5]
	v_ashrrev_i32_e32 v31, 31, v30
	v_lshl_add_u64 v[30:31], v[30:31], 1, v[64:65]
	v_lshrrev_b32_e32 v30, 16, v220
	v_cndmask_b32_e64 v32, v33, v32, s[6:7]
	v_ashrrev_i32_e32 v33, 31, v32
	v_lshl_add_u64 v[32:33], v[32:33], 1, v[64:65]
	v_mov_b32_e32 v38, v221
	v_mov_b32_e32 v39, v222
	v_cndmask_b32_e64 v31, 0, 1.0, s[4:5]
	v_lshlrev_b32_e32 v34, 16, v36
	v_and_b32_e32 v35, 0xffff0000, v36
	v_pk_fma_f32 v[26:27], v[128:129], v[34:35], v[26:27] op_sel_hi:[0,1,1]
	v_lshlrev_b32_e32 v36, 16, v37
	v_and_b32_e32 v37, 0xffff0000, v37
	v_pk_fma_f32 v[28:29], v[128:129], v[36:37], v[28:29] op_sel_hi:[0,1,1]
	v_mov_b32_e32 v36, v225
	v_mov_b32_e32 v37, v226
	s_nop 0
	v_lshlrev_b32_e32 v30, 16, v30
	v_mul_f32_e32 v31, v31, v30
	v_and_b32_e32 v30, 0xffff, v223
	v_cndmask_b32_e64 v32, 1.0, 0, s[6:7]
	s_nop 0
	v_and_b32_e32 v40, 0xffff0000, v38
	v_lshlrev_b32_e32 v41, 16, v39
	v_and_b32_e32 v39, 0xffff0000, v39
	s_nop 0
	v_lshlrev_b32_e32 v30, 16, v30
	v_mul_f32_e32 v33, v32, v30
	v_mov_b32_e32 v30, v40
	v_lshlrev_b32_e32 v32, 16, v38
	v_pk_mul_f32 v[30:31], v[122:123], v[30:31]
	v_mov_b32_e32 v38, v41
	v_pk_fma_f32 v[30:31], v[122:123], v[32:33], v[30:31] op_sel:[0,0,1] op_sel_hi:[1,0,0]
	v_mov_b32_e32 v32, v39
	v_pk_fma_f32 v[30:31], v[126:127], v[40:41], v[30:31] op_sel_hi:[0,1,1]
	v_pk_add_f32 v[30:31], v[124:125], v[30:31] op_sel_hi:[0,1]
	v_pk_mul_f32 v[26:27], v[30:31], v[26:27]
	v_pk_mul_f32 v[30:31], v[122:123], v[38:39] op_sel_hi:[0,1]
	v_pk_fma_f32 v[30:31], v[0:1], v[40:41], v[30:31] op_sel_hi:[0,1,1]
	v_pk_fma_f32 v[30:31], v[126:127], v[32:33], v[30:31] op_sel_hi:[0,1,1]
	v_pk_add_f32 v[30:31], v[124:125], v[30:31] op_sel_hi:[0,1]
	v_pk_mul_f32 v[28:29], v[28:29], v[30:31]
	v_cvt_pk_bf16_f32 v26, v26, v27
	v_cvt_pk_bf16_f32 v27, v28, v29
	v_add_u32_e32 v28, 0xa0, v66
	global_store_dwordx2 v[62:63], v[26:27], off offset:288
	v_and_b32_e32 v26, 60, v28
	v_add_u32_e32 v29, 0xa4, v66
	v_cmp_ne_u32_e64 s[4:5], 0, v26
	v_and_b32_e32 v26, 60, v29
	v_cmp_eq_u32_e64 s[6:7], 0, v26
	v_subbrev_co_u32_e64 v26, s[8:9], 0, v28, s[4:5]
	v_ashrrev_i32_e32 v27, 31, v26
	v_lshl_add_u64 v[26:27], v[26:27], 1, v[64:65]
	v_lshrrev_b32_e32 v26, 16, v224
	v_cndmask_b32_e64 v27, 0, 1.0, s[4:5]
	v_and_b32_e32 v38, 0xffff0000, v36
	v_mov_b32_e32 v32, v38
	v_lshlrev_b32_e32 v30, 16, v36
	v_lshlrev_b32_e32 v39, 16, v37
	v_and_b32_e32 v37, 0xffff0000, v37
	v_mov_b32_e32 v36, v39
	s_nop 0
	v_lshlrev_b32_e32 v26, 16, v26
	v_mul_f32_e32 v33, v27, v26
	v_cndmask_b32_e64 v26, v29, v28, s[6:7]
	v_ashrrev_i32_e32 v27, 31, v26
	v_lshl_add_u64 v[26:27], v[26:27], 1, v[64:65]
	v_and_b32_e32 v26, 0xffff, v227
	v_cndmask_b32_e64 v27, 1.0, 0, s[6:7]
	v_pk_mul_f32 v[32:33], v[122:123], v[32:33]
	s_nop 0
	v_lshlrev_b32_e32 v26, 16, v26
	v_mul_f32_e32 v31, v27, v26
	ds_read2_b64 v[26:29], v67 offset0:40 offset1:44
	v_pk_fma_f32 v[32:33], v[122:123], v[30:31], v[32:33] op_sel:[0,0,1] op_sel_hi:[1,0,0]
	v_mov_b32_e32 v30, v37
	v_pk_fma_f32 v[32:33], v[126:127], v[38:39], v[32:33] op_sel_hi:[0,1,1]
	v_pk_add_f32 v[32:33], v[124:125], v[32:33] op_sel_hi:[0,1]
	s_waitcnt lgkmcnt(0)
	v_lshlrev_b32_e32 v34, 16, v26
	v_and_b32_e32 v35, 0xffff0000, v26
	v_pk_fma_f32 v[22:23], v[128:129], v[34:35], v[22:23] op_sel_hi:[0,1,1]
	v_pk_mul_f32 v[22:23], v[32:33], v[22:23]
	v_pk_mul_f32 v[32:33], v[122:123], v[36:37] op_sel_hi:[0,1]
	v_pk_fma_f32 v[32:33], v[0:1], v[38:39], v[32:33] op_sel_hi:[0,1,1]
	v_lshlrev_b32_e32 v26, 16, v27
	v_and_b32_e32 v27, 0xffff0000, v27
	v_pk_fma_f32 v[30:31], v[126:127], v[30:31], v[32:33] op_sel_hi:[0,1,1]
	v_pk_add_f32 v[30:31], v[124:125], v[30:31] op_sel_hi:[0,1]
	v_pk_fma_f32 v[24:25], v[128:129], v[26:27], v[24:25] op_sel_hi:[0,1,1]
	v_pk_mul_f32 v[24:25], v[24:25], v[30:31]
	v_cvt_pk_bf16_f32 v22, v22, v23
	v_cvt_pk_bf16_f32 v23, v24, v25
	v_add_u32_e32 v24, 0xb0, v66
	global_store_dwordx2 v[62:63], v[22:23], off offset:320
	v_and_b32_e32 v22, 60, v24
	v_add_u32_e32 v26, 0xb4, v66
	v_cmp_ne_u32_e64 s[4:5], 0, v22
	v_and_b32_e32 v22, 60, v26
	v_cmp_eq_u32_e64 s[6:7], 0, v22
	v_subbrev_co_u32_e64 v22, s[8:9], 0, v24, s[4:5]
	v_ashrrev_i32_e32 v23, 31, v22
	v_lshl_add_u64 v[22:23], v[22:23], 1, v[64:65]
	v_lshrrev_b32_e32 v22, 16, v228
	v_cndmask_b32_e64 v23, 0, 1.0, s[4:5]
	v_lshlrev_b32_e32 v30, 16, v28
	v_and_b32_e32 v31, 0xffff0000, v28
	v_and_b32_e32 v27, 0xffff0000, v29
	v_pk_fma_f32 v[18:19], v[128:129], v[30:31], v[18:19] op_sel_hi:[0,1,1]
	s_nop 0
	v_lshlrev_b32_e32 v22, 16, v22
	v_mul_f32_e32 v25, v23, v22
	v_cndmask_b32_e64 v22, v26, v24, s[6:7]
	v_ashrrev_i32_e32 v23, 31, v22
	v_lshl_add_u64 v[22:23], v[22:23], 1, v[64:65]
	v_and_b32_e32 v22, 0xffff, v231
	v_lshlrev_b32_e32 v26, 16, v29
; DI float bf2f(bfu v) { return __uint_as_float(((unsigned)v) << 16); }
; DI unsigned pack2(float a, float b) { f32x2_t v = {a, b}; bf16x2_t r = __builtin_convertvector(v, bf16x2_t); return __builtin_bit_cast(unsigned, r); }
; DI float lo16(unsigned u) { return __uint_as_float(u << 16); }
; DI float hi16(unsigned u) { return __uint_as_float(u & 0xffff0000u); }
; template <int L>
; DI void hyena_job(const PX& p, int l, int c, unsigned char* smem) {
;     ...
; #pragma unroll
;     for (int m = 0; m < TPW; m++) {
;       const int t0 = 16 * (w * TPW + m) + 4 * kq_o;
;       const bfu* zr = zx2 + b * L;
;       const uint2 mid = *(const uint2*)(zr + t0);
;       const bool lv = (t0 % RL != 0), rv = ((t0 + 4) % RL != 0);
;       const float lft = bf2f(zr[lv ? t0 - 1 : t0]) * (lv ? 1.f : 0.f);
;       const float rgt = bf2f(zr[rv ? t0 + 4 : t0]) * (rv ? 1.f : 0.f);
;       float z[6];
;       z[0] = lft; z[5] = rgt; z[1] = lo16(mid.x); z[2] = hi16(mid.x); z[3] = lo16(mid.y); z[4] = hi16(mid.y);
;       const uint2 vu = *(const uint2*)(U + b * USTR + t0);
;       const float vv[4] = {lo16(vu.x), hi16(vu.x), lo16(vu.y), hi16(vu.y)};
;       float y2[4];
; #pragma unroll
;       for (int r = 0; r < 4; r++) {
;         const float x2 = w2[0] * z[r] + w2[1] * z[r + 1] + w2[2] * z[r + 2] + w2[3];
;         y2[r] = x2 * (acc[m][r] + bias1 * vv[r]);
;       }
;       uint2 o2; o2.x = pack2(y2[0], y2[1]); o2.y = pack2(y2[2], y2[3]);
;       *(uint2*)(yrow + b * L + t0) = o2;
;     }
	v_mov_b32_e32 v28, v229
	v_mov_b32_e32 v29, v230
	v_cndmask_b32_e64 v23, 1.0, 0, s[6:7]
	v_pk_fma_f32 v[20:21], v[128:129], v[26:27], v[20:21] op_sel_hi:[0,1,1]
	s_nop 0
	v_lshlrev_b32_e32 v22, 16, v22
	v_mul_f32_e32 v23, v23, v22
	s_nop 0
	v_and_b32_e32 v32, 0xffff0000, v28
	v_mov_b32_e32 v24, v32
	v_lshlrev_b32_e32 v22, 16, v28
	v_pk_mul_f32 v[24:25], v[122:123], v[24:25]
	v_lshlrev_b32_e32 v33, 16, v29
	v_pk_fma_f32 v[24:25], v[122:123], v[22:23], v[24:25] op_sel:[0,0,1] op_sel_hi:[1,0,0]
	v_and_b32_e32 v29, 0xffff0000, v29
	v_pk_fma_f32 v[24:25], v[126:127], v[32:33], v[24:25] op_sel_hi:[0,1,1]
	v_mov_b32_e32 v28, v33
	v_pk_add_f32 v[24:25], v[124:125], v[24:25] op_sel_hi:[0,1]
	v_pk_mul_f32 v[18:19], v[24:25], v[18:19]
	v_pk_mul_f32 v[24:25], v[122:123], v[28:29] op_sel_hi:[0,1]
	v_pk_fma_f32 v[24:25], v[0:1], v[32:33], v[24:25] op_sel_hi:[0,1,1]
	v_mov_b32_e32 v22, v29
	v_pk_fma_f32 v[22:23], v[126:127], v[22:23], v[24:25] op_sel_hi:[0,1,1]
	v_pk_add_f32 v[22:23], v[124:125], v[22:23] op_sel_hi:[0,1]
	v_pk_mul_f32 v[20:21], v[20:21], v[22:23]
	v_cvt_pk_bf16_f32 v18, v18, v19
	v_cvt_pk_bf16_f32 v19, v20, v21
	v_add_u32_e32 v21, 0xc4, v66
	global_store_dwordx2 v[62:63], v[18:19], off offset:352
	v_add_u32_e32 v20, 0xc0, v66
	v_and_b32_e32 v18, 60, v21
	v_cmp_eq_u32_e64 s[4:5], 0, v18
	v_subbrev_co_u32_e32 v18, vcc, 0, v20, vcc
	v_ashrrev_i32_e32 v19, 31, v18
	v_lshl_add_u64 v[18:19], v[18:19], 1, v[64:65]
	v_lshrrev_b32_e32 v18, 16, v232
	s_nop 0
	v_mov_b32_e32 v28, v233
	v_mov_b32_e32 v29, v234
	s_nop 0
	v_lshlrev_b32_e32 v18, 16, v18
	v_mul_f32_e32 v23, v74, v18
	v_cndmask_b32_e64 v18, v21, v20, s[4:5]
	v_ashrrev_i32_e32 v19, 31, v18
	v_lshl_add_u64 v[18:19], v[18:19], 1, v[64:65]
	v_and_b32_e32 v18, 0xffff, v235
	v_cndmask_b32_e64 v19, 1.0, 0, s[4:5]
	s_nop 0
	v_and_b32_e32 v30, 0xffff0000, v28
	v_mov_b32_e32 v22, v30
	v_lshlrev_b32_e32 v24, 16, v28
	v_pk_mul_f32 v[22:23], v[122:123], v[22:23]
	v_lshlrev_b32_e32 v31, 16, v29
	v_and_b32_e32 v29, 0xffff0000, v29
	v_mov_b32_e32 v28, v31
	s_nop 0
	v_lshlrev_b32_e32 v18, 16, v18
	v_mul_f32_e32 v25, v19, v18
	ds_read2_b64 v[18:21], v67 offset0:48 offset1:52
	v_pk_fma_f32 v[22:23], v[122:123], v[24:25], v[22:23] op_sel:[0,0,1] op_sel_hi:[1,0,0]
	v_mov_b32_e32 v24, v29
	v_pk_fma_f32 v[22:23], v[126:127], v[30:31], v[22:23] op_sel_hi:[0,1,1]
	v_pk_add_f32 v[22:23], v[124:125], v[22:23] op_sel_hi:[0,1]
	s_waitcnt lgkmcnt(0)
	v_lshlrev_b32_e32 v26, 16, v18
	v_and_b32_e32 v27, 0xffff0000, v18
	v_pk_fma_f32 v[14:15], v[128:129], v[26:27], v[14:15] op_sel_hi:[0,1,1]
	v_pk_mul_f32 v[14:15], v[22:23], v[14:15]
	v_pk_mul_f32 v[22:23], v[122:123], v[28:29] op_sel_hi:[0,1]
	v_pk_fma_f32 v[22:23], v[0:1], v[30:31], v[22:23] op_sel_hi:[0,1,1]
	v_lshlrev_b32_e32 v18, 16, v19
	v_and_b32_e32 v19, 0xffff0000, v19
	v_pk_fma_f32 v[22:23], v[126:127], v[24:25], v[22:23] op_sel_hi:[0,1,1]
	v_pk_add_f32 v[22:23], v[124:125], v[22:23] op_sel_hi:[0,1]
	v_pk_fma_f32 v[16:17], v[128:129], v[18:19], v[16:17] op_sel_hi:[0,1,1]
	v_pk_mul_f32 v[16:17], v[16:17], v[22:23]
	v_cvt_pk_bf16_f32 v14, v14, v15
	v_cvt_pk_bf16_f32 v15, v16, v17
	v_add_u32_e32 v16, 0xd0, v66
	global_store_dwordx2 v[62:63], v[14:15], off offset:384
	v_and_b32_e32 v14, 60, v16
	v_add_u32_e32 v17, 0xd4, v66
	v_cmp_ne_u32_e32 vcc, 0, v14
	v_and_b32_e32 v14, 60, v17
	v_cmp_eq_u32_e64 s[4:5], 0, v14
	v_subbrev_co_u32_e64 v14, s[6:7], 0, v16, vcc
	v_ashrrev_i32_e32 v15, 31, v14
	v_lshl_add_u64 v[14:15], v[14:15], 1, v[64:65]
	v_lshrrev_b32_e32 v14, 16, v236
	v_cndmask_b32_e64 v16, v17, v16, s[4:5]
	v_ashrrev_i32_e32 v17, 31, v16
	v_lshl_add_u64 v[16:17], v[16:17], 1, v[64:65]
	v_mov_b32_e32 v22, v237
	v_mov_b32_e32 v23, v238
	v_cndmask_b32_e64 v15, 0, 1.0, vcc
	v_lshlrev_b32_e32 v18, 16, v20
	v_and_b32_e32 v19, 0xffff0000, v20
	v_pk_fma_f32 v[10:11], v[128:129], v[18:19], v[10:11] op_sel_hi:[0,1,1]
	v_lshlrev_b32_e32 v20, 16, v21
	v_and_b32_e32 v21, 0xffff0000, v21
	v_pk_fma_f32 v[12:13], v[128:129], v[20:21], v[12:13] op_sel_hi:[0,1,1]
	v_mov_b32_e32 v20, v241
	v_mov_b32_e32 v21, v242
	s_nop 0
	v_lshlrev_b32_e32 v14, 16, v14
	v_mul_f32_e32 v15, v15, v14
	v_and_b32_e32 v14, 0xffff, v239
	v_cndmask_b32_e64 v16, 1.0, 0, s[4:5]
	s_nop 0
	v_and_b32_e32 v24, 0xffff0000, v22
	v_lshlrev_b32_e32 v25, 16, v23
	v_and_b32_e32 v23, 0xffff0000, v23
	s_nop 0
	v_lshlrev_b32_e32 v14, 16, v14
	v_mul_f32_e32 v17, v16, v14
	v_mov_b32_e32 v14, v24
	v_lshlrev_b32_e32 v16, 16, v22
	v_pk_mul_f32 v[14:15], v[122:123], v[14:15]
	v_mov_b32_e32 v22, v25
	v_pk_fma_f32 v[14:15], v[122:123], v[16:17], v[14:15] op_sel:[0,0,1] op_sel_hi:[1,0,0]
	v_mov_b32_e32 v16, v23
	v_pk_fma_f32 v[14:15], v[126:127], v[24:25], v[14:15] op_sel_hi:[0,1,1]
	v_pk_add_f32 v[14:15], v[124:125], v[14:15] op_sel_hi:[0,1]
	v_pk_mul_f32 v[10:11], v[14:15], v[10:11]
	v_pk_mul_f32 v[14:15], v[122:123], v[22:23] op_sel_hi:[0,1]
	v_pk_fma_f32 v[14:15], v[0:1], v[24:25], v[14:15] op_sel_hi:[0,1,1]
	v_pk_fma_f32 v[14:15], v[126:127], v[16:17], v[14:15] op_sel_hi:[0,1,1]
	v_pk_add_f32 v[14:15], v[124:125], v[14:15] op_sel_hi:[0,1]
	v_pk_mul_f32 v[12:13], v[12:13], v[14:15]
	v_cvt_pk_bf16_f32 v10, v10, v11
	v_cvt_pk_bf16_f32 v11, v12, v13
	v_add_u32_e32 v12, 0xe0, v66
	global_store_dwordx2 v[62:63], v[10:11], off offset:416
	v_and_b32_e32 v10, 60, v12
	v_add_u32_e32 v13, 0xe4, v66
	v_cmp_ne_u32_e32 vcc, 0, v10
	v_and_b32_e32 v10, 60, v13
	v_cmp_eq_u32_e64 s[4:5], 0, v10
	v_subbrev_co_u32_e64 v10, s[6:7], 0, v12, vcc
	v_ashrrev_i32_e32 v11, 31, v10
	v_lshl_add_u64 v[10:11], v[10:11], 1, v[64:65]
	v_lshrrev_b32_e32 v10, 16, v240
	v_cndmask_b32_e64 v11, 0, 1.0, vcc
	v_and_b32_e32 v22, 0xffff0000, v20
	v_mov_b32_e32 v16, v22
	v_lshlrev_b32_e32 v14, 16, v20
	v_lshlrev_b32_e32 v23, 16, v21
	v_and_b32_e32 v21, 0xffff0000, v21
	v_mov_b32_e32 v20, v23
	s_nop 0
	v_lshlrev_b32_e32 v10, 16, v10
	v_mul_f32_e32 v17, v11, v10
	v_cndmask_b32_e64 v10, v13, v12, s[4:5]
	v_ashrrev_i32_e32 v11, 31, v10
	v_lshl_add_u64 v[10:11], v[10:11], 1, v[64:65]
	v_and_b32_e32 v10, 0xffff, v243
	v_cndmask_b32_e64 v11, 1.0, 0, s[4:5]
	v_pk_mul_f32 v[16:17], v[122:123], v[16:17]
	s_nop 0
	v_lshlrev_b32_e32 v10, 16, v10
	v_mul_f32_e32 v15, v11, v10
	ds_read2_b64 v[10:13], v67 offset0:56 offset1:60
	v_pk_fma_f32 v[16:17], v[122:123], v[14:15], v[16:17] op_sel:[0,0,1] op_sel_hi:[1,0,0]
	v_mov_b32_e32 v14, v21
	v_pk_fma_f32 v[16:17], v[126:127], v[22:23], v[16:17] op_sel_hi:[0,1,1]
	v_pk_add_f32 v[16:17], v[124:125], v[16:17] op_sel_hi:[0,1]
	s_waitcnt lgkmcnt(0)
; DI float bf2f(bfu v) { return __uint_as_float(((unsigned)v) << 16); }
; DI unsigned pack2(float a, float b) { f32x2_t v = {a, b}; bf16x2_t r = __builtin_convertvector(v, bf16x2_t); return __builtin_bit_cast(unsigned, r); }
; DI float lo16(unsigned u) { return __uint_as_float(u << 16); }
; DI float hi16(unsigned u) { return __uint_as_float(u & 0xffff0000u); }
; template <int L>
; DI void hyena_job(const PX& p, int l, int c, unsigned char* smem) {
;     ...
; #pragma unroll
;     for (int m = 0; m < TPW; m++) {
;       const int t0 = 16 * (w * TPW + m) + 4 * kq_o;
;       const bfu* zr = zx2 + b * L;
;       const uint2 mid = *(const uint2*)(zr + t0);
;       const bool lv = (t0 % RL != 0), rv = ((t0 + 4) % RL != 0);
;       const float lft = bf2f(zr[lv ? t0 - 1 : t0]) * (lv ? 1.f : 0.f);
;       const float rgt = bf2f(zr[rv ? t0 + 4 : t0]) * (rv ? 1.f : 0.f);
;       float z[6];
;       z[0] = lft; z[5] = rgt; z[1] = lo16(mid.x); z[2] = hi16(mid.x); z[3] = lo16(mid.y); z[4] = hi16(mid.y);
;       const uint2 vu = *(const uint2*)(U + b * USTR + t0);
;       const float vv[4] = {lo16(vu.x), hi16(vu.x), lo16(vu.y), hi16(vu.y)};
;       float y2[4];
; #pragma unroll
;       for (int r = 0; r < 4; r++) {
;         const float x2 = w2[0] * z[r] + w2[1] * z[r + 1] + w2[2] * z[r + 2] + w2[3];
;         y2[r] = x2 * (acc[m][r] + bias1 * vv[r]);
;       }
;       uint2 o2; o2.x = pack2(y2[0], y2[1]); o2.y = pack2(y2[2], y2[3]);
;       *(uint2*)(yrow + b * L + t0) = o2;
;     }
	v_lshlrev_b32_e32 v18, 16, v10
	v_and_b32_e32 v19, 0xffff0000, v10
	v_pk_fma_f32 v[6:7], v[128:129], v[18:19], v[6:7] op_sel_hi:[0,1,1]
	v_pk_mul_f32 v[6:7], v[16:17], v[6:7]
	v_pk_mul_f32 v[16:17], v[122:123], v[20:21] op_sel_hi:[0,1]
	v_pk_fma_f32 v[16:17], v[0:1], v[22:23], v[16:17] op_sel_hi:[0,1,1]
	v_lshlrev_b32_e32 v10, 16, v11
	v_and_b32_e32 v11, 0xffff0000, v11
	v_pk_fma_f32 v[14:15], v[126:127], v[14:15], v[16:17] op_sel_hi:[0,1,1]
	v_pk_add_f32 v[14:15], v[124:125], v[14:15] op_sel_hi:[0,1]
	v_pk_fma_f32 v[8:9], v[128:129], v[10:11], v[8:9] op_sel_hi:[0,1,1]
	v_pk_mul_f32 v[8:9], v[8:9], v[14:15]
	v_add_u32_e32 v0, 0xf0, v66
	v_cvt_pk_bf16_f32 v6, v6, v7
	v_cvt_pk_bf16_f32 v7, v8, v9
	v_and_b32_e32 v8, 60, v0
	v_add_u32_e32 v10, 0xf4, v66
	v_cmp_ne_u32_e32 vcc, 0, v8
	v_and_b32_e32 v8, 60, v10
	v_cmp_eq_u32_e64 s[4:5], 0, v8
	v_subbrev_co_u32_e64 v8, s[6:7], 0, v0, vcc
	v_ashrrev_i32_e32 v9, 31, v8
	v_cndmask_b32_e64 v10, v10, v0, s[4:5]
	global_store_dwordx2 v[62:63], v[6:7], off offset:448
	v_lshl_add_u64 v[8:9], v[8:9], 1, v[64:65]
	v_ashrrev_i32_e32 v11, 31, v10
	v_lshrrev_b32_e32 v8, 16, v244
	v_lshl_add_u64 v[10:11], v[10:11], 1, v[64:65]
	v_mov_b32_e32 v6, v245
	v_mov_b32_e32 v7, v246
	v_and_b32_e32 v0, 0xffff, v247
	v_cndmask_b32_e64 v9, 0, 1.0, vcc
	v_lshlrev_b32_e32 v14, 16, v12
	v_and_b32_e32 v15, 0xffff0000, v12
	v_pk_fma_f32 v[2:3], v[128:129], v[14:15], v[2:3] op_sel_hi:[0,1,1]
	v_and_b32_e32 v10, 0xffff0000, v13
	v_mov_b32_e32 v129, v126
	v_lshlrev_b32_e32 v12, 16, v13
	v_mul_f32_e32 v12, v128, v12
	v_mov_b32_e32 v13, v124
	s_nop 0
	v_lshlrev_b32_e32 v8, 16, v8
	v_mul_f32_e32 v9, v9, v8
	v_cndmask_b32_e64 v8, 1.0, 0, s[4:5]
	s_nop 0
	v_lshlrev_b32_e32 v0, 16, v0
	v_mul_f32_e32 v11, v8, v0
	v_and_b32_e32 v8, 0xffff0000, v6
	v_lshlrev_b32_e32 v0, 16, v6
	v_lshlrev_b32_e32 v6, 16, v7
	v_pk_mul_f32 v[16:17], v[122:123], v[8:9]
	v_mov_b32_e32 v9, v6
	v_pk_fma_f32 v[16:17], v[122:123], v[0:1], v[16:17] op_sel:[0,0,1] op_sel_hi:[1,0,0]
	v_and_b32_e32 v7, 0xffff0000, v7
	v_pk_fma_f32 v[14:15], v[126:127], v[8:9], v[16:17] op_sel_hi:[0,1,1]
	v_pk_add_f32 v[14:15], v[124:125], v[14:15] op_sel_hi:[0,1]
	v_pk_mul_f32 v[14:15], v[14:15], v[2:3]
	v_mov_b32_e32 v2, v122
	v_mov_b32_e32 v3, v126
	v_pk_mul_f32 v[2:3], v[2:3], v[6:7]
	v_mov_b32_e32 v9, v122
	v_fma_f32 v0, v123, v8, v2
	v_add_f32_e32 v0, v3, v0
	v_add_f32_e32 v2, v124, v0
	v_mov_b32_e32 v8, v123
	v_mul_f32_e32 v0, v123, v6
	v_pk_fma_f32 v[6:7], v[8:9], v[6:7], v[0:1] op_sel_hi:[1,1,0]
	v_cvt_pk_bf16_f32 v0, v14, v15
	v_mov_b32_e32 v6, v5
	v_pk_fma_f32 v[6:7], v[128:129], v[10:11], v[6:7]
	global_store_dword v[62:63], v0, off offset:480
	v_mov_b32_e32 v5, v7
	v_pk_add_f32 v[4:5], v[4:5], v[12:13]
	v_mov_b32_e32 v3, v6
	v_pk_mul_f32 v[2:3], v[2:3], v[4:5]
	v_lshl_add_u64 v[6:7], v[62:63], 0, s[0:1]
	s_branch .LBB0_515

; #define TIDX(p) ((p).wv * 64 + (int)__builtin_amdgcn_mbcnt_hi(~0u, __builtin_amdgcn_mbcnt_lo(~0u, 0u)))
; DI void gbar(const PX& p, unsigned target) {
;   asm volatile("s_waitcnt vmcnt(0)" ::: "memory");
;   __syncthreads();
;   if (TIDX(p) == 0) {
;     unsigned* cnt = (unsigned*)(p.ws + OFF_CNT) + 32;
;     __builtin_amdgcn_fence(__ATOMIC_RELEASE, "agent");
;     asm volatile("s_waitcnt vmcnt(0)" ::: "memory");
;     __hip_atomic_fetch_add(cnt, 1u, __ATOMIC_RELAXED, __HIP_MEMORY_SCOPE_AGENT);
;     unsigned spins = 0;
;     while (__hip_atomic_load(cnt, __ATOMIC_RELAXED, __HIP_MEMORY_SCOPE_AGENT) < target) {
;       __builtin_amdgcn_s_sleep(2);
;       if (++spins > (1u << 26)) break;
;     }
;     __builtin_amdgcn_fence(__ATOMIC_ACQUIRE, "agent");
;     asm volatile("s_waitcnt vmcnt(0)" ::: "memory");
;   }
;   __syncthreads();
; }
; __global__ void __launch_bounds__(NTHR) mega(P p0, int ph_lo, int ph_hi) {
;     ...
;       const int nrep = (((REP >> i) & 1) && (i != 5 || l == 0)) ? 2 : 1;
;       for (int rp = 0; rp < nrep; rp++) {
;       if (rp) grid.sync();
.LBB0_1108:
	v_readlane_b32 s1, v255, 9
	s_mov_b32 s3, 0x4000
	s_lshr_b32 s3, s3, s1
	s_and_b32 s3, s3, 1
	s_cbranch_scc0 .Lprobe_none
	v_readlane_b32 s2, v255, 61
	s_cmp_ge_u32 s2, 1
	s_cbranch_scc1 .Lprobe_done
	s_add_i32 s2, s2, 1
	v_writelane_b32 v255, s2, 61
	v_readlane_b32 s2, v255, 60
	s_lshl_b32 s3, 1, s1
	s_or_b32 s2, s2, s3
	v_writelane_b32 v255, s2, 60
	v_readlane_b32 s6, v255, 62
	s_add_i32 s6, s6, 1
	v_writelane_b32 v255, s6, 62
	s_mul_i32 s6, s6, s83
	s_waitcnt vmcnt(0) lgkmcnt(0)
	v_sub_u32_e32 v0, 0, v211
	v_readlane_b32 s7, v255, 7
	s_nop 0
	s_barrier
	v_cmp_eq_u32_e32 vcc, s7, v0
	s_and_saveexec_b64 s[4:5], vcc
	s_cbranch_execz .Lprobe_join
	buffer_wbl2 sc1
	s_waitcnt vmcnt(0)
	v_mov_b32_e32 v0, 1
	v_readlane_b32 s2, v254, 42
	v_readlane_b32 s3, v254, 43
	s_nop 4
	global_atomic_add v1, v0, s[2:3] offset:32
